# P8 conv epilogue: 128 ds_bpermute_b32 row rotations per tile-wave replaced by v_mov_b32_dpp row_ror (no LDS round trip)
# baseline (speedup 1.0000x reference)
; __device__ __forceinline__ u32x4 pack8(const f32x4 a, const f32x4 b) { u32x4 w; w.x = cvt_pk_bf16(a[0], a[1]); w.y = cvt_pk_bf16(a[2], a[3]); w.z = cvt_pk_bf16(b[0], b[1]); w.w = cvt_pk_bf16(b[2], b[3]); return w; }
;     __device__ __forceinline__ void operator()(const f32x4 (&acc)[2][2][4][2], const Unit& u, int wr, int wc, int fr, int fq) const {
;         const int lane = threadIdx.x & 63;
;         const int f0 = u.pn * 128 + wc * 32 + 8 * fq;
;         f32x4 w0[2], w1[2], w2[2], bb[2];
; #pragma unroll
;         for (int n = 0; n < 2; ++n) { w0[n] = *(const f32x4*)(cw + f0 + 4 * n); w1[n] = *(const f32x4*)(cw + DFF + f0 + 4 * n); w2[n] = *(const f32x4*)(cw + 2 * DFF + f0 + 4 * n); bb[n] = *(const f32x4*)(cb + f0 + 4 * n); }
;         const int src1 = (lane & 48) | ((fr - 1) & 15), src2 = (lane & 48) | ((fr - 2) & 15);
; #pragma unroll
;         for (int ai = 0; ai < 2; ++ai) {
;             const int jb = u.pm * 4 + ai * 2 + wr;
;             f32x4 p1[2], p2[2];
; #pragma unroll
;             for (int n = 0; n < 2; ++n) { p1[n] = (f32x4){0.f, 0.f, 0.f, 0.f}; p2[n] = p1[n]; }
; #pragma unroll
;             for (int m = 0; m < 4; ++m) {
;                 f32x4 o[2];
; #pragma unroll
;                 for (int n = 0; n < 2; ++n) { f32x4 r1, r2;
; #pragma unroll
;                     for (int e = 0; e < 4; ++e) { const float a0 = acc[ai][0][m][n][e]; r1[e] = __shfl(a0, src1); r2[e] = __shfl(a0, src2); }
;                     f32x4 a1, a2;
; #pragma unroll
;                     for (int e = 0; e < 4; ++e) { a1[e] = fr >= 1 ? r1[e] : p1[n][e]; a2[e] = fr >= 2 ? r2[e] : p2[n][e]; }
;                     p1[n] = r1; p2[n] = r2;
;                     const f32x4 c = bb[n] + w0[n] * a2 + w1[n] * a1 + w2[n] * acc[ai][0][m][n];
; #pragma unroll
;                     for (int e = 0; e < 4; ++e) { const float x = c[e]; const float uu = 0.7978845608028654f * (x + 0.044715f * x * x * x);
;                         const float gl = x * __builtin_amdgcn_rcpf(1.f + __builtin_amdgcn_exp2f(-2.885390081777927f * uu)); o[n][e] = gl * acc[ai][1][m][n][e]; } }
;                 const int row = u.pm * BM + ai * HALF + wr * 64 + m * 16 + fr;
;                 if (!(m == 0 && fr < 2)) *(u32x4*)(G + (size_t)row * DFF + f0) = pack8(o[0], o[1]);
.LBB0_911:
	v_lshl_or_b32 v186, s67, 7, v175
	v_ashrrev_i32_e32 v187, 31, v186
	v_lshlrev_b64 v[188:189], 2, v[186:187]
	v_lshl_add_u64 v[86:87], s[24:25], 0, v[188:189]
	v_lshl_add_u64 v[90:91], s[40:41], 0, v[188:189]
	v_lshl_add_u64 v[94:95], s[44:45], 0, v[188:189]
	v_lshl_add_u64 v[110:111], s[26:27], 0, v[188:189]
	global_load_dwordx4 v[82:85], v[86:87], off offset:16
	global_load_dwordx4 v[98:101], v[86:87], off
	s_nop 0
	global_load_dwordx4 v[86:89], v[90:91], off offset:16
	global_load_dwordx4 v[102:105], v[90:91], off
	s_nop 0
	global_load_dwordx4 v[90:93], v[94:95], off offset:16
	global_load_dwordx4 v[106:109], v[94:95], off
	s_nop 0
	global_load_dwordx4 v[94:97], v[110:111], off offset:16
	s_nop 0
	global_load_dwordx4 v[110:113], v[110:111], off
	s_nop 1
	v_mov_b32_dpp v200, v158 row_ror:1 row_mask:0xf bank_mask:0xf
	v_mov_b32_dpp v198, v158 row_ror:2 row_mask:0xf bank_mask:0xf
	v_mov_b32_dpp v201, v159 row_ror:1 row_mask:0xf bank_mask:0xf
	v_mov_b32_dpp v199, v159 row_ror:2 row_mask:0xf bank_mask:0xf
	v_mov_b32_dpp v196, v160 row_ror:1 row_mask:0xf bank_mask:0xf
	v_mov_b32_dpp v194, v160 row_ror:2 row_mask:0xf bank_mask:0xf
	v_mov_b32_dpp v197, v161 row_ror:1 row_mask:0xf bank_mask:0xf
	v_mov_b32_dpp v195, v161 row_ror:2 row_mask:0xf bank_mask:0xf
	v_mov_b32_dpp v192, v154 row_ror:1 row_mask:0xf bank_mask:0xf
	v_mov_b32_dpp v190, v154 row_ror:2 row_mask:0xf bank_mask:0xf
	v_mov_b32_dpp v193, v155 row_ror:1 row_mask:0xf bank_mask:0xf
	v_mov_b32_dpp v191, v155 row_ror:2 row_mask:0xf bank_mask:0xf
	v_mov_b32_dpp v204, v156 row_ror:1 row_mask:0xf bank_mask:0xf
	v_mov_b32_dpp v202, v156 row_ror:2 row_mask:0xf bank_mask:0xf
	v_mov_b32_dpp v205, v157 row_ror:1 row_mask:0xf bank_mask:0xf
	v_mov_b32_dpp v203, v157 row_ror:2 row_mask:0xf bank_mask:0xf
	v_lshl_add_u32 v215, s66, 8, v165
	s_and_saveexec_b64 s[68:69], s[8:9]
	s_xor_b64 s[68:69], exec, s[68:69]
	s_cbranch_execz .LBB0_913
	s_waitcnt vmcnt(0) lgkmcnt(0)
	v_pk_fma_f32 v[216:217], v[84:85], v[202:203], v[96:97]
	s_nop 0
	v_pk_fma_f32 v[216:217], v[88:89], v[204:205], v[216:217]
	s_nop 0
	v_pk_fma_f32 v[216:217], v[156:157], v[92:93], v[216:217]
	s_nop 0
	v_mul_f32_e32 v218, 0x3d372713, v217
	v_mul_f32_e32 v218, v217, v218
	v_mul_f32_e32 v219, 0x3d372713, v216
	v_fma_f32 v218, v217, v218, v217
	v_mul_f32_e32 v219, v216, v219
	v_mul_f32_e32 v218, 0x3f4c422a, v218
	v_fma_f32 v219, v216, v219, v216
	v_mul_f32_e32 v218, 0xc038aa3b, v218
	v_mul_f32_e32 v219, 0x3f4c422a, v219
	v_exp_f32_e32 v218, v218
	v_mul_f32_e32 v219, 0xc038aa3b, v219
	v_exp_f32_e32 v220, v219
	v_add_f32_e32 v218, 1.0, v218
	v_rcp_f32_e32 v219, v218
	v_add_f32_e32 v218, 1.0, v220
	v_rcp_f32_e32 v218, v218
	s_nop 0
	v_pk_mul_f32 v[216:217], v[216:217], v[218:219]
	v_pk_fma_f32 v[218:219], v[98:99], v[198:199], v[110:111]
	s_nop 0
	v_pk_fma_f32 v[218:219], v[102:103], v[200:201], v[218:219]
	s_nop 0
	v_pk_fma_f32 v[218:219], v[158:159], v[106:107], v[218:219]
	s_nop 0
	v_mul_f32_e32 v220, 0x3d372713, v218
	v_mul_f32_e32 v220, v218, v220
	v_fma_f32 v220, v218, v220, v218
	v_mul_f32_e32 v220, 0x3f4c422a, v220
	v_mul_f32_e32 v220, 0xc038aa3b, v220
	v_exp_f32_e32 v222, v220
	v_mul_f32_e32 v220, 0x3d372713, v219
	v_mul_f32_e32 v220, v219, v220
	v_fma_f32 v220, v219, v220, v219
	v_mul_f32_e32 v220, 0x3f4c422a, v220
	v_mul_f32_e32 v220, 0xc038aa3b, v220
	v_exp_f32_e32 v223, v220
	v_pk_mul_f32 v[220:221], v[148:149], v[216:217]
	v_add_f32_e32 v216, 1.0, v222
	v_rcp_f32_e32 v216, v216
	v_add_f32_e32 v217, 1.0, v223
	v_pk_fma_f32 v[222:223], v[100:101], v[194:195], v[112:113]
	v_rcp_f32_e32 v217, v217
	v_pk_fma_f32 v[222:223], v[104:105], v[196:197], v[222:223]
	v_pk_mul_f32 v[216:217], v[218:219], v[216:217]
	v_pk_fma_f32 v[222:223], v[160:161], v[108:109], v[222:223]
	v_pk_mul_f32 v[216:217], v[150:151], v[216:217]
	v_mul_f32_e32 v224, 0x3d372713, v222
	v_mul_f32_e32 v225, 0x3d372713, v223
	v_mul_f32_e32 v224, v222, v224
	v_mul_f32_e32 v225, v223, v225
	v_fma_f32 v224, v222, v224, v222
	v_fma_f32 v225, v223, v225, v223
	v_mul_f32_e32 v224, 0x3f4c422a, v224
	v_mul_f32_e32 v225, 0x3f4c422a, v225
	v_mul_f32_e32 v224, 0xc038aa3b, v224
	v_mul_f32_e32 v225, 0xc038aa3b, v225
	v_exp_f32_e32 v224, v224
	v_exp_f32_e32 v225, v225
	v_cvt_pk_bf16_f32 v216, v216, v217
	v_add_f32_e32 v218, 1.0, v224
	v_add_f32_e32 v219, 1.0, v225
	v_pk_fma_f32 v[224:225], v[82:83], v[190:191], v[94:95]
	v_rcp_f32_e32 v218, v218
	v_pk_fma_f32 v[224:225], v[86:87], v[192:193], v[224:225]
	v_rcp_f32_e32 v219, v219
	v_pk_fma_f32 v[224:225], v[154:155], v[90:91], v[224:225]
	v_pk_mul_f32 v[218:219], v[222:223], v[218:219]
	v_mul_f32_e32 v226, 0x3d372713, v225
	v_mul_f32_e32 v226, v225, v226
	v_mul_f32_e32 v227, 0x3d372713, v224
	v_fma_f32 v226, v225, v226, v225
	v_mul_f32_e32 v227, v224, v227
	v_mul_f32_e32 v226, 0x3f4c422a, v226
	v_fma_f32 v227, v224, v227, v224
	v_mul_f32_e32 v226, 0xc038aa3b, v226
	v_mul_f32_e32 v227, 0x3f4c422a, v227
	v_exp_f32_e32 v226, v226
	v_mul_f32_e32 v227, 0xc038aa3b, v227
	v_exp_f32_e32 v228, v227
	v_pk_mul_f32 v[218:219], v[152:153], v[218:219]
	v_add_f32_e32 v226, 1.0, v226
	v_rcp_f32_e32 v227, v226
	v_add_f32_e32 v226, 1.0, v228
	v_rcp_f32_e32 v226, v226
	v_cvt_pk_bf16_f32 v217, v218, v219
	v_cvt_pk_bf16_f32 v219, v220, v221
	v_mov_b64_e32 v[220:221], s[10:11]
	v_pk_mul_f32 v[222:223], v[224:225], v[226:227]
	v_mad_i64_i32 v[220:221], s[70:71], v215, s79, v[220:221]
	v_pk_mul_f32 v[222:223], v[146:147], v[222:223]
	v_lshl_add_u64 v[220:221], v[186:187], 1, v[220:221]
	v_cvt_pk_bf16_f32 v218, v222, v223
	global_store_dwordx4 v[220:221], v[216:219], off

; __device__ __forceinline__ u32x4 pack8(const f32x4 a, const f32x4 b) { u32x4 w; w.x = cvt_pk_bf16(a[0], a[1]); w.y = cvt_pk_bf16(a[2], a[3]); w.z = cvt_pk_bf16(b[0], b[1]); w.w = cvt_pk_bf16(b[2], b[3]); return w; }
;     __device__ __forceinline__ void operator()(const f32x4 (&acc)[2][2][4][2], const Unit& u, int wr, int wc, int fr, int fq) const {
;     ...
;             for (int m = 0; m < 4; ++m) {
;                 f32x4 o[2];
; #pragma unroll
;                 for (int n = 0; n < 2; ++n) { f32x4 r1, r2;
; #pragma unroll
;                     for (int e = 0; e < 4; ++e) { const float a0 = acc[ai][0][m][n][e]; r1[e] = __shfl(a0, src1); r2[e] = __shfl(a0, src2); }
;                     f32x4 a1, a2;
; #pragma unroll
;                     for (int e = 0; e < 4; ++e) { a1[e] = fr >= 1 ? r1[e] : p1[n][e]; a2[e] = fr >= 2 ? r2[e] : p2[n][e]; }
;                     p1[n] = r1; p2[n] = r2;
;                     const f32x4 c = bb[n] + w0[n] * a2 + w1[n] * a1 + w2[n] * acc[ai][0][m][n];
; #pragma unroll
;                     for (int e = 0; e < 4; ++e) { const float x = c[e]; const float uu = 0.7978845608028654f * (x + 0.044715f * x * x * x);
;                         const float gl = x * __builtin_amdgcn_rcpf(1.f + __builtin_amdgcn_exp2f(-2.885390081777927f * uu)); o[n][e] = gl * acc[ai][1][m][n][e]; } }
;                 const int row = u.pm * BM + ai * HALF + wr * 64 + m * 16 + fr;
;                 if (!(m == 0 && fr < 2)) *(u32x4*)(G + (size_t)row * DFF + f0) = pack8(o[0], o[1]);
.LBB0_915:
	s_or_b64 exec, exec, s[70:71]
	s_nop 1
	v_mov_b32_dpp v159, v141 row_ror:2 row_mask:0xf bank_mask:0xf
	v_mov_b32_dpp v160, v140 row_ror:2 row_mask:0xf bank_mask:0xf
	v_mov_b32_dpp v157, v141 row_ror:1 row_mask:0xf bank_mask:0xf
	v_mov_b32_dpp v158, v140 row_ror:1 row_mask:0xf bank_mask:0xf
	v_mov_b32_dpp v151, v142 row_ror:2 row_mask:0xf bank_mask:0xf
	s_waitcnt lgkmcnt(0)
	v_cndmask_b32_e64 v149, v203, v159, s[8:9]
	v_cndmask_b32_e64 v148, v202, v160, s[8:9]
	v_cndmask_b32_e64 v147, v157, v205, s[0:1]
	v_cndmask_b32_e64 v146, v158, v204, s[0:1]
	s_waitcnt vmcnt(0)
	v_pk_fma_f32 v[148:149], v[84:85], v[148:149], v[96:97]
	s_nop 1
	v_mov_b32_dpp v153, v143 row_ror:2 row_mask:0xf bank_mask:0xf
	v_pk_fma_f32 v[146:147], v[88:89], v[146:147], v[148:149]
	s_nop 1
	v_mov_b32_dpp v150, v142 row_ror:1 row_mask:0xf bank_mask:0xf
	v_pk_fma_f32 v[140:141], v[140:141], v[92:93], v[146:147]
	s_nop 1
	v_mov_b32_dpp v152, v143 row_ror:1 row_mask:0xf bank_mask:0xf
	v_mul_f32_e32 v146, 0x3d372713, v141
	v_mul_f32_e32 v146, v141, v146
	v_mul_f32_e32 v147, 0x3d372713, v140
	v_fma_f32 v146, v141, v146, v141
	v_mul_f32_e32 v147, v140, v147
	v_mul_f32_e32 v146, 0x3f4c422a, v146
	v_fma_f32 v147, v140, v147, v140
	v_mul_f32_e32 v146, 0xc038aa3b, v146
	v_mul_f32_e32 v147, 0x3f4c422a, v147
	v_exp_f32_e32 v146, v146
	v_mul_f32_e32 v147, 0xc038aa3b, v147
	v_exp_f32_e32 v148, v147
	s_waitcnt lgkmcnt(2)
	v_cndmask_b32_e64 v149, v199, v153, s[8:9]
	v_add_f32_e32 v146, 1.0, v146
	v_rcp_f32_e32 v147, v146
	v_add_f32_e32 v146, 1.0, v148
	v_rcp_f32_e32 v146, v146
	v_cndmask_b32_e64 v148, v198, v151, s[8:9]
	v_pk_fma_f32 v[148:149], v[98:99], v[148:149], v[110:111]
	s_nop 1
	v_mov_b32_dpp v155, v144 row_ror:2 row_mask:0xf bank_mask:0xf
	v_pk_mul_f32 v[140:141], v[140:141], v[146:147]
	s_waitcnt lgkmcnt(1)
	v_cndmask_b32_e64 v147, v152, v201, s[0:1]
	v_cndmask_b32_e64 v146, v150, v200, s[0:1]
	v_pk_fma_f32 v[146:147], v[102:103], v[146:147], v[148:149]
	s_nop 1
	v_mov_b32_dpp v161, v145 row_ror:2 row_mask:0xf bank_mask:0xf
	v_pk_fma_f32 v[142:143], v[142:143], v[106:107], v[146:147]
	s_nop 1
	v_mov_b32_dpp v154, v144 row_ror:1 row_mask:0xf bank_mask:0xf
	v_mul_f32_e32 v146, 0x3d372713, v142
	v_mul_f32_e32 v147, 0x3d372713, v143
	v_mul_f32_e32 v146, v142, v146
	v_mul_f32_e32 v147, v143, v147
	v_fma_f32 v146, v142, v146, v142
	v_fma_f32 v147, v143, v147, v143
	v_mul_f32_e32 v146, 0x3f4c422a, v146
	v_mul_f32_e32 v147, 0x3f4c422a, v147
	s_nop 1
	v_mov_b32_dpp v156, v145 row_ror:1 row_mask:0xf bank_mask:0xf
	v_mul_f32_e32 v146, 0xc038aa3b, v146
	v_mul_f32_e32 v147, 0xc038aa3b, v147
	v_exp_f32_e32 v146, v146
	v_exp_f32_e32 v147, v147
	s_waitcnt lgkmcnt(2)
	v_cndmask_b32_e64 v149, v195, v161, s[8:9]
	v_cndmask_b32_e64 v148, v194, v155, s[8:9]
	v_pk_mul_f32 v[132:133], v[132:133], v[140:141]
	v_add_f32_e32 v140, 1.0, v146
	v_add_f32_e32 v141, 1.0, v147
	s_waitcnt lgkmcnt(0)
	v_cndmask_b32_e64 v147, v156, v197, s[0:1]
	v_cndmask_b32_e64 v146, v154, v196, s[0:1]
	v_pk_fma_f32 v[148:149], v[100:101], v[148:149], v[112:113]
	s_nop 1
	v_mov_b32_dpp v203, v138 row_ror:2 row_mask:0xf bank_mask:0xf
	v_pk_fma_f32 v[146:147], v[104:105], v[146:147], v[148:149]
	s_nop 1
	v_mov_b32_dpp v205, v139 row_ror:2 row_mask:0xf bank_mask:0xf
	v_pk_fma_f32 v[144:145], v[144:145], v[108:109], v[146:147]
	s_nop 1
	v_mov_b32_dpp v202, v138 row_ror:1 row_mask:0xf bank_mask:0xf
	v_mul_f32_e32 v146, 0x3d372713, v144
	v_mul_f32_e32 v147, 0x3d372713, v145
	v_mul_f32_e32 v146, v144, v146
	v_mul_f32_e32 v147, v145, v147
	v_fma_f32 v146, v144, v146, v144
	v_fma_f32 v147, v145, v147, v145
	v_mul_f32_e32 v146, 0x3f4c422a, v146
	v_mul_f32_e32 v147, 0x3f4c422a, v147
	s_nop 1
	v_mov_b32_dpp v204, v139 row_ror:1 row_mask:0xf bank_mask:0xf
	v_mul_f32_e32 v146, 0xc038aa3b, v146
	v_mul_f32_e32 v147, 0xc038aa3b, v147
	v_rcp_f32_e32 v140, v140
	v_rcp_f32_e32 v141, v141
	v_exp_f32_e32 v146, v146
	v_exp_f32_e32 v147, v147
	s_waitcnt lgkmcnt(2)
	v_cndmask_b32_e64 v149, v191, v205, s[8:9]
	v_cndmask_b32_e64 v148, v190, v203, s[8:9]
	v_pk_mul_f32 v[140:141], v[142:143], v[140:141]
	v_add_f32_e32 v142, 1.0, v146
	v_add_f32_e32 v143, 1.0, v147
	s_waitcnt lgkmcnt(0)
	v_cndmask_b32_e64 v147, v204, v193, s[0:1]
	v_cndmask_b32_e64 v146, v202, v192, s[0:1]
	v_pk_fma_f32 v[148:149], v[82:83], v[148:149], v[94:95]
	v_rcp_f32_e32 v142, v142
	v_pk_fma_f32 v[146:147], v[86:87], v[146:147], v[148:149]
	v_rcp_f32_e32 v143, v143
	v_pk_fma_f32 v[138:139], v[138:139], v[90:91], v[146:147]
	v_pk_mul_f32 v[134:135], v[134:135], v[140:141]
	v_mul_f32_e32 v146, 0x3d372713, v139
	v_mul_f32_e32 v146, v139, v146
	v_mul_f32_e32 v147, 0x3d372713, v138
	v_fma_f32 v146, v139, v146, v139
	v_mul_f32_e32 v147, v138, v147
	v_mul_f32_e32 v146, 0x3f4c422a, v146
	v_fma_f32 v147, v138, v147, v138
	v_mul_f32_e32 v146, 0xc038aa3b, v146
	v_mul_f32_e32 v147, 0x3f4c422a, v147
	v_exp_f32_e32 v146, v146
	v_mul_f32_e32 v147, 0xc038aa3b, v147
	v_exp_f32_e32 v148, v147
	v_pk_mul_f32 v[140:141], v[144:145], v[142:143]
	v_add_f32_e32 v146, 1.0, v146
	v_rcp_f32_e32 v147, v146
	v_add_f32_e32 v146, 1.0, v148
	v_rcp_f32_e32 v146, v146
	s_nop 1
	v_mov_b32_dpp v148, v124 row_ror:2 row_mask:0xf bank_mask:0xf
	v_pk_mul_f32 v[136:137], v[136:137], v[140:141]
	s_nop 1
	v_mov_b32_dpp v145, v125 row_ror:1 row_mask:0xf bank_mask:0xf
	v_pk_mul_f32 v[138:139], v[138:139], v[146:147]
	s_nop 1
	v_mov_b32_dpp v147, v125 row_ror:2 row_mask:0xf bank_mask:0xf
	v_mov_b32_dpp v146, v124 row_ror:1 row_mask:0xf bank_mask:0xf
	v_pk_mul_f32 v[130:131], v[130:131], v[138:139]
	v_or_b32_e32 v138, 16, v215
	v_cvt_pk_bf16_f32 v134, v134, v135
	v_cvt_pk_bf16_f32 v135, v136, v137
	v_cvt_pk_bf16_f32 v137, v132, v133
	v_mov_b64_e32 v[132:133], s[10:11]
	v_cvt_pk_bf16_f32 v136, v130, v131
	v_mad_i64_i32 v[138:139], s[70:71], v138, s79, v[132:133]
	v_lshlrev_b64 v[130:131], 1, v[186:187]
	v_lshl_add_u64 v[138:139], v[138:139], 0, v[130:131]
	global_store_dwordx4 v[138:139], v[134:137], off
	s_nop 1
	v_mov_b32_dpp v139, v126 row_ror:2 row_mask:0xf bank_mask:0xf
	v_mov_b32_dpp v141, v127 row_ror:2 row_mask:0xf bank_mask:0xf
	s_waitcnt lgkmcnt(3)
; __device__ __forceinline__ u32x4 pack8(const f32x4 a, const f32x4 b) { u32x4 w; w.x = cvt_pk_bf16(a[0], a[1]); w.y = cvt_pk_bf16(a[2], a[3]); w.z = cvt_pk_bf16(b[0], b[1]); w.w = cvt_pk_bf16(b[2], b[3]); return w; }
;     __device__ __forceinline__ void operator()(const f32x4 (&acc)[2][2][4][2], const Unit& u, int wr, int wc, int fr, int fq) const {
;     ...
;             for (int m = 0; m < 4; ++m) {
;                 f32x4 o[2];
; #pragma unroll
;                 for (int n = 0; n < 2; ++n) { f32x4 r1, r2;
; #pragma unroll
;                     for (int e = 0; e < 4; ++e) { const float a0 = acc[ai][0][m][n][e]; r1[e] = __shfl(a0, src1); r2[e] = __shfl(a0, src2); }
;                     f32x4 a1, a2;
; #pragma unroll
;                     for (int e = 0; e < 4; ++e) { a1[e] = fr >= 1 ? r1[e] : p1[n][e]; a2[e] = fr >= 2 ? r2[e] : p2[n][e]; }
;                     p1[n] = r1; p2[n] = r2;
;                     const f32x4 c = bb[n] + w0[n] * a2 + w1[n] * a1 + w2[n] * acc[ai][0][m][n];
; #pragma unroll
;                     for (int e = 0; e < 4; ++e) { const float x = c[e]; const float uu = 0.7978845608028654f * (x + 0.044715f * x * x * x);
;                         const float gl = x * __builtin_amdgcn_rcpf(1.f + __builtin_amdgcn_exp2f(-2.885390081777927f * uu)); o[n][e] = gl * acc[ai][1][m][n][e]; } }
;                 const int row = u.pm * BM + ai * HALF + wr * 64 + m * 16 + fr;
;                 if (!(m == 0 && fr < 2)) *(u32x4*)(G + (size_t)row * DFF + f0) = pack8(o[0], o[1]);
	v_cndmask_b32_e64 v137, v159, v147, s[8:9]
	v_cndmask_b32_e64 v136, v160, v148, s[8:9]
	v_cndmask_b32_e64 v135, v145, v157, s[0:1]
	s_waitcnt lgkmcnt(2)
	v_cndmask_b32_e64 v134, v146, v158, s[0:1]
	v_pk_fma_f32 v[136:137], v[84:85], v[136:137], v[96:97]
	s_nop 1
	v_mov_b32_dpp v138, v126 row_ror:1 row_mask:0xf bank_mask:0xf
	v_pk_fma_f32 v[134:135], v[88:89], v[134:135], v[136:137]
	s_nop 1
	v_mov_b32_dpp v140, v127 row_ror:1 row_mask:0xf bank_mask:0xf
	v_pk_fma_f32 v[124:125], v[124:125], v[92:93], v[134:135]
	s_waitcnt lgkmcnt(2)
	v_cndmask_b32_e64 v137, v153, v141, s[8:9]
	v_mul_f32_e32 v134, 0x3d372713, v125
	v_mul_f32_e32 v134, v125, v134
	v_mul_f32_e32 v135, 0x3d372713, v124
	v_fma_f32 v134, v125, v134, v125
	v_mul_f32_e32 v135, v124, v135
	v_mul_f32_e32 v134, 0x3f4c422a, v134
	v_fma_f32 v135, v124, v135, v124
	v_mul_f32_e32 v134, 0xc038aa3b, v134
	v_mul_f32_e32 v135, 0x3f4c422a, v135
	v_exp_f32_e32 v134, v134
	v_mul_f32_e32 v135, 0xc038aa3b, v135
	v_exp_f32_e32 v136, v135
	s_nop 1
	v_mov_b32_dpp v143, v128 row_ror:2 row_mask:0xf bank_mask:0xf
	v_add_f32_e32 v134, 1.0, v134
	v_rcp_f32_e32 v135, v134
	v_add_f32_e32 v134, 1.0, v136
	v_rcp_f32_e32 v134, v134
	v_cndmask_b32_e64 v136, v151, v139, s[8:9]
	v_pk_fma_f32 v[136:137], v[98:99], v[136:137], v[110:111]
	s_nop 1
	v_mov_b32_dpp v149, v129 row_ror:2 row_mask:0xf bank_mask:0xf
	v_pk_mul_f32 v[124:125], v[124:125], v[134:135]
	s_waitcnt lgkmcnt(2)
	v_cndmask_b32_e64 v135, v140, v152, s[0:1]
	v_cndmask_b32_e64 v134, v138, v150, s[0:1]
	v_pk_fma_f32 v[134:135], v[102:103], v[134:135], v[136:137]
	s_nop 1
	v_mov_b32_dpp v142, v128 row_ror:1 row_mask:0xf bank_mask:0xf
	v_pk_fma_f32 v[126:127], v[126:127], v[106:107], v[134:135]
	s_nop 1
	v_mov_b32_dpp v144, v129 row_ror:1 row_mask:0xf bank_mask:0xf
	v_mul_f32_e32 v134, 0x3d372713, v126
	v_mul_f32_e32 v135, 0x3d372713, v127
	v_mul_f32_e32 v134, v126, v134
	v_mul_f32_e32 v135, v127, v135
	v_fma_f32 v134, v126, v134, v126
	v_fma_f32 v135, v127, v135, v127
	v_mul_f32_e32 v134, 0x3f4c422a, v134
	v_mul_f32_e32 v135, 0x3f4c422a, v135
	v_mul_f32_e32 v134, 0xc038aa3b, v134
	v_mul_f32_e32 v135, 0xc038aa3b, v135
	v_exp_f32_e32 v134, v134
	v_exp_f32_e32 v135, v135
	s_waitcnt lgkmcnt(2)
	v_cndmask_b32_e64 v137, v161, v149, s[8:9]
	v_cndmask_b32_e64 v136, v155, v143, s[8:9]
	v_pk_mul_f32 v[124:125], v[116:117], v[124:125]
	v_add_f32_e32 v116, 1.0, v134
	v_add_f32_e32 v117, 1.0, v135
	s_waitcnt lgkmcnt(0)
	v_cndmask_b32_e64 v135, v144, v156, s[0:1]
	v_cndmask_b32_e64 v134, v142, v154, s[0:1]
	v_pk_fma_f32 v[136:137], v[100:101], v[136:137], v[112:113]
	s_nop 1
	v_mov_b32_dpp v158, v122 row_ror:2 row_mask:0xf bank_mask:0xf
	v_pk_fma_f32 v[134:135], v[104:105], v[134:135], v[136:137]
	s_nop 1
	v_mov_b32_dpp v160, v123 row_ror:2 row_mask:0xf bank_mask:0xf
	v_pk_fma_f32 v[128:129], v[128:129], v[108:109], v[134:135]
	s_nop 1
	v_mov_b32_dpp v157, v122 row_ror:1 row_mask:0xf bank_mask:0xf
	v_mul_f32_e32 v134, 0x3d372713, v128
	v_mul_f32_e32 v135, 0x3d372713, v129
	v_mul_f32_e32 v134, v128, v134
	v_mul_f32_e32 v135, v129, v135
	v_fma_f32 v134, v128, v134, v128
	v_fma_f32 v135, v129, v135, v129
	v_mul_f32_e32 v134, 0x3f4c422a, v134
	v_mul_f32_e32 v135, 0x3f4c422a, v135
	s_nop 1
	v_mov_b32_dpp v159, v123 row_ror:1 row_mask:0xf bank_mask:0xf
	v_mul_f32_e32 v134, 0xc038aa3b, v134
	v_mul_f32_e32 v135, 0xc038aa3b, v135
	v_rcp_f32_e32 v116, v116
	v_rcp_f32_e32 v117, v117
	v_exp_f32_e32 v134, v134
	v_exp_f32_e32 v135, v135
	s_waitcnt lgkmcnt(2)
	v_cndmask_b32_e64 v137, v205, v160, s[8:9]
	v_cndmask_b32_e64 v136, v203, v158, s[8:9]
	v_pk_mul_f32 v[116:117], v[126:127], v[116:117]
	v_add_f32_e32 v126, 1.0, v134
	v_add_f32_e32 v127, 1.0, v135
	s_waitcnt lgkmcnt(0)
	v_cndmask_b32_e64 v135, v159, v204, s[0:1]
	v_cndmask_b32_e64 v134, v157, v202, s[0:1]
	v_pk_fma_f32 v[136:137], v[82:83], v[136:137], v[94:95]
	v_rcp_f32_e32 v126, v126
	v_pk_fma_f32 v[134:135], v[86:87], v[134:135], v[136:137]
	v_rcp_f32_e32 v127, v127
	v_pk_fma_f32 v[122:123], v[122:123], v[90:91], v[134:135]
	v_pk_mul_f32 v[116:117], v[118:119], v[116:117]
	v_mul_f32_e32 v134, 0x3d372713, v123
	v_mul_f32_e32 v134, v123, v134
	v_mul_f32_e32 v135, 0x3d372713, v122
	v_fma_f32 v134, v123, v134, v123
	v_mul_f32_e32 v135, v122, v135
	v_mul_f32_e32 v134, 0x3f4c422a, v134
	v_fma_f32 v135, v122, v135, v122
	v_mul_f32_e32 v134, 0xc038aa3b, v134
	v_mul_f32_e32 v135, 0x3f4c422a, v135
	v_exp_f32_e32 v134, v134
	v_mul_f32_e32 v135, 0xc038aa3b, v135
	v_exp_f32_e32 v136, v135
	v_pk_mul_f32 v[118:119], v[128:129], v[126:127]
	v_add_f32_e32 v134, 1.0, v134
	v_rcp_f32_e32 v135, v134
	v_add_f32_e32 v134, 1.0, v136
	v_rcp_f32_e32 v134, v134
	v_pk_mul_f32 v[118:119], v[120:121], v[118:119]
	s_nop 1
	v_mov_b32_dpp v126, v81 row_ror:2 row_mask:0xf bank_mask:0xf
	v_mov_b32_dpp v129, v71 row_ror:2 row_mask:0xf bank_mask:0xf
	v_pk_mul_f32 v[120:121], v[122:123], v[134:135]
	v_or_b32_e32 v122, 32, v215
	v_pk_mul_f32 v[120:121], v[114:115], v[120:121]
	v_cvt_pk_bf16_f32 v115, v118, v119
	v_mad_i64_i32 v[118:119], s[70:71], v122, s79, v[132:133]
	v_cvt_pk_bf16_f32 v114, v116, v117
	v_cvt_pk_bf16_f32 v116, v120, v121
	v_cvt_pk_bf16_f32 v117, v124, v125
	v_lshl_add_u64 v[118:119], v[118:119], 0, v[130:131]
	global_store_dwordx4 v[118:119], v[114:117], off
	s_nop 1
	v_mov_b32_dpp v114, v73 row_ror:1 row_mask:0xf bank_mask:0xf
	v_mov_b32_dpp v116, v72 row_ror:1 row_mask:0xf bank_mask:0xf
	v_mov_b32_dpp v117, v73 row_ror:2 row_mask:0xf bank_mask:0xf
	v_mov_b32_dpp v125, v72 row_ror:2 row_mask:0xf bank_mask:0xf
	v_mov_b32_dpp v118, v78 row_ror:1 row_mask:0xf bank_mask:0xf
	s_waitcnt lgkmcnt(4)
	v_cndmask_b32_e64 v115, v114, v145, s[0:1]
	s_waitcnt lgkmcnt(3)
; __device__ __forceinline__ u32x4 pack8(const f32x4 a, const f32x4 b) { u32x4 w; w.x = cvt_pk_bf16(a[0], a[1]); w.y = cvt_pk_bf16(a[2], a[3]); w.z = cvt_pk_bf16(b[0], b[1]); w.w = cvt_pk_bf16(b[2], b[3]); return w; }
;     __device__ __forceinline__ void operator()(const f32x4 (&acc)[2][2][4][2], const Unit& u, int wr, int wc, int fr, int fq) const {
;     ...
;             for (int m = 0; m < 4; ++m) {
;                 f32x4 o[2];
; #pragma unroll
;                 for (int n = 0; n < 2; ++n) { f32x4 r1, r2;
; #pragma unroll
;                     for (int e = 0; e < 4; ++e) { const float a0 = acc[ai][0][m][n][e]; r1[e] = __shfl(a0, src1); r2[e] = __shfl(a0, src2); }
;                     f32x4 a1, a2;
; #pragma unroll
;                     for (int e = 0; e < 4; ++e) { a1[e] = fr >= 1 ? r1[e] : p1[n][e]; a2[e] = fr >= 2 ? r2[e] : p2[n][e]; }
;                     p1[n] = r1; p2[n] = r2;
;                     const f32x4 c = bb[n] + w0[n] * a2 + w1[n] * a1 + w2[n] * acc[ai][0][m][n];
; #pragma unroll
;                     for (int e = 0; e < 4; ++e) { const float x = c[e]; const float uu = 0.7978845608028654f * (x + 0.044715f * x * x * x);
;                         const float gl = x * __builtin_amdgcn_rcpf(1.f + __builtin_amdgcn_exp2f(-2.885390081777927f * uu)); o[n][e] = gl * acc[ai][1][m][n][e]; } }
;                 const int row = u.pm * BM + ai * HALF + wr * 64 + m * 16 + fr;
;                 if (!(m == 0 && fr < 2)) *(u32x4*)(G + (size_t)row * DFF + f0) = pack8(o[0], o[1]);
;                 if (m == 0 && fr < 2) { float* ah = AH + ((size_t)jb * 4 + 2 + fr) * DFF + f0; *(f32x4*)ah = acc[ai][0][0][0]; *(f32x4*)(ah + 4) = acc[ai][0][0][1];
;                     float* bh = BH + ((size_t)jb * 2 + fr) * DFF + f0; *(f32x4*)bh = acc[ai][1][0][0]; *(f32x4*)(bh + 4) = acc[ai][1][0][1]; }
;                 if (m == 3 && fr >= 14) { float* ah = AH + ((size_t)jb * 4 + (fr - 14)) * DFF + f0; *(f32x4*)ah = acc[ai][0][3][0]; *(f32x4*)(ah + 4) = acc[ai][0][3][1]; }
	v_cndmask_b32_e64 v114, v116, v146, s[0:1]
	s_waitcnt lgkmcnt(2)
	v_cndmask_b32_e64 v117, v147, v117, s[8:9]
	s_waitcnt lgkmcnt(1)
	v_cndmask_b32_e64 v116, v148, v125, s[8:9]
	v_pk_fma_f32 v[116:117], v[84:85], v[116:117], v[96:97]
	s_nop 1
	v_mov_b32_dpp v120, v78 row_ror:2 row_mask:0xf bank_mask:0xf
	v_pk_fma_f32 v[114:115], v[88:89], v[114:115], v[116:117]
	s_nop 1
	v_mov_b32_dpp v119, v79 row_ror:1 row_mask:0xf bank_mask:0xf
	v_pk_fma_f32 v[114:115], v[72:73], v[92:93], v[114:115]
	s_nop 1
	v_mov_b32_dpp v121, v79 row_ror:2 row_mask:0xf bank_mask:0xf
	v_mul_f32_e32 v116, 0x3d372713, v115
	v_mul_f32_e32 v116, v115, v116
	v_mul_f32_e32 v117, 0x3d372713, v114
	v_fma_f32 v116, v115, v116, v115
	v_mul_f32_e32 v117, v114, v117
	v_mul_f32_e32 v116, 0x3f4c422a, v116
	v_fma_f32 v117, v114, v117, v114
	v_mul_f32_e32 v116, 0xc038aa3b, v116
	v_mul_f32_e32 v117, 0x3f4c422a, v117
	v_exp_f32_e32 v116, v116
	v_mul_f32_e32 v117, 0xc038aa3b, v117
	v_exp_f32_e32 v125, v117
	s_nop 1
	v_mov_b32_dpp v123, v80 row_ror:2 row_mask:0xf bank_mask:0xf
	v_add_f32_e32 v116, 1.0, v116
	v_rcp_f32_e32 v117, v116
	v_add_f32_e32 v116, 1.0, v125
	v_rcp_f32_e32 v116, v116
	s_nop 1
	v_mov_b32_dpp v122, v80 row_ror:1 row_mask:0xf bank_mask:0xf
	v_mov_b32_dpp v124, v81 row_ror:1 row_mask:0xf bank_mask:0xf
	v_mov_b32_dpp v125, v70 row_ror:2 row_mask:0xf bank_mask:0xf
	v_pk_mul_f32 v[114:115], v[114:115], v[116:117]
	s_waitcnt lgkmcnt(5)
	v_cndmask_b32_e64 v117, v119, v140, s[0:1]
	v_cndmask_b32_e64 v116, v118, v138, s[0:1]
	s_waitcnt lgkmcnt(4)
	v_cndmask_b32_e64 v119, v141, v121, s[8:9]
	v_cndmask_b32_e64 v118, v139, v120, s[8:9]
	v_pk_fma_f32 v[118:119], v[98:99], v[118:119], v[110:111]
	v_cndmask_b32_e64 v121, v149, v126, s[8:9]
	v_pk_fma_f32 v[116:117], v[102:103], v[116:117], v[118:119]
	s_waitcnt lgkmcnt(3)
	v_cndmask_b32_e64 v120, v143, v123, s[8:9]
	v_pk_fma_f32 v[116:117], v[78:79], v[106:107], v[116:117]
	v_pk_mul_f32 v[114:115], v[68:69], v[114:115]
	v_mul_f32_e32 v118, 0x3d372713, v116
	v_mul_f32_e32 v119, 0x3d372713, v117
	v_mul_f32_e32 v118, v116, v118
	v_mul_f32_e32 v119, v117, v119
	v_fma_f32 v118, v116, v118, v116
	v_fma_f32 v119, v117, v119, v117
	v_mul_f32_e32 v118, 0x3f4c422a, v118
	v_mul_f32_e32 v119, 0x3f4c422a, v119
	v_mul_f32_e32 v118, 0xc038aa3b, v118
	v_mul_f32_e32 v119, 0xc038aa3b, v119
	v_exp_f32_e32 v118, v118
	v_exp_f32_e32 v119, v119
	v_pk_fma_f32 v[120:121], v[100:101], v[120:121], v[112:113]
	s_nop 1
	v_mov_b32_dpp v127, v70 row_ror:1 row_mask:0xf bank_mask:0xf
	v_add_f32_e32 v68, 1.0, v118
	v_add_f32_e32 v69, 1.0, v119
	s_waitcnt lgkmcnt(2)
	v_cndmask_b32_e64 v119, v124, v144, s[0:1]
	v_cndmask_b32_e64 v118, v122, v142, s[0:1]
	v_pk_fma_f32 v[118:119], v[104:105], v[118:119], v[120:121]
	s_nop 1
	v_mov_b32_dpp v128, v71 row_ror:1 row_mask:0xf bank_mask:0xf
	v_pk_fma_f32 v[118:119], v[80:81], v[108:109], v[118:119]
	v_rcp_f32_e32 v68, v68
	v_mul_f32_e32 v120, 0x3d372713, v118
	v_mul_f32_e32 v121, 0x3d372713, v119
	v_mul_f32_e32 v120, v118, v120
	v_mul_f32_e32 v121, v119, v121
	v_fma_f32 v120, v118, v120, v118
	v_fma_f32 v121, v119, v121, v119
	v_mul_f32_e32 v120, 0x3f4c422a, v120
	v_mul_f32_e32 v121, 0x3f4c422a, v121
	v_mul_f32_e32 v120, 0xc038aa3b, v120
	v_mul_f32_e32 v121, 0xc038aa3b, v121
	v_rcp_f32_e32 v69, v69
	v_exp_f32_e32 v120, v120
	v_exp_f32_e32 v121, v121
	v_cndmask_b32_e64 v123, v160, v129, s[8:9]
	s_waitcnt lgkmcnt(2)
	v_cndmask_b32_e64 v122, v158, v125, s[8:9]
	v_pk_mul_f32 v[68:69], v[116:117], v[68:69]
	v_add_f32_e32 v116, 1.0, v120
	v_add_f32_e32 v117, 1.0, v121
	s_waitcnt lgkmcnt(0)
	v_cndmask_b32_e64 v121, v128, v159, s[0:1]
	v_cndmask_b32_e64 v120, v127, v157, s[0:1]
	v_pk_fma_f32 v[122:123], v[82:83], v[122:123], v[94:95]
	v_rcp_f32_e32 v116, v116
	v_pk_fma_f32 v[120:121], v[86:87], v[120:121], v[122:123]
	v_rcp_f32_e32 v117, v117
	v_pk_fma_f32 v[120:121], v[70:71], v[90:91], v[120:121]
	v_pk_mul_f32 v[68:69], v[74:75], v[68:69]
	v_mul_f32_e32 v122, 0x3d372713, v121
	v_mul_f32_e32 v122, v121, v122
	v_mul_f32_e32 v123, 0x3d372713, v120
	v_fma_f32 v122, v121, v122, v121
	v_mul_f32_e32 v123, v120, v123
	v_mul_f32_e32 v122, 0x3f4c422a, v122
	v_fma_f32 v123, v120, v123, v120
	v_mul_f32_e32 v122, 0xc038aa3b, v122
	v_mul_f32_e32 v123, 0x3f4c422a, v123
	v_exp_f32_e32 v122, v122
	v_mul_f32_e32 v123, 0xc038aa3b, v123
	v_exp_f32_e32 v124, v123
	v_pk_mul_f32 v[74:75], v[118:119], v[116:117]
	v_add_f32_e32 v122, 1.0, v122
	v_rcp_f32_e32 v123, v122
	v_add_f32_e32 v122, 1.0, v124
	v_rcp_f32_e32 v122, v122
	v_pk_mul_f32 v[74:75], v[76:77], v[74:75]
	v_or_b32_e32 v116, 48, v215
	v_pk_mul_f32 v[76:77], v[120:121], v[122:123]
	s_nop 0
	v_pk_mul_f32 v[76:77], v[66:67], v[76:77]
	v_cvt_pk_bf16_f32 v67, v74, v75
	v_mad_i64_i32 v[74:75], s[70:71], v116, s79, v[132:133]
	v_cvt_pk_bf16_f32 v66, v68, v69
	v_cvt_pk_bf16_f32 v68, v76, v77
	v_cvt_pk_bf16_f32 v69, v114, v115
	v_lshl_add_u64 v[74:75], v[74:75], 0, v[130:131]
	global_store_dwordx4 v[74:75], v[66:69], off
	s_and_saveexec_b64 s[70:71], s[4:5]
	s_cbranch_execz .LBB0_917
	v_lshl_add_u64 v[66:67], s[68:69], 0, v[176:177]
	v_mov_b64_e32 v[68:69], s[14:15]
	v_mad_u64_u32 v[68:69], s[68:69], v66, s80, v[68:69]
	v_mad_i32_i24 v69, v67, s80, v69
	v_lshl_add_u64 v[66:67], v[186:187], 2, v[68:69]
	global_store_dwordx4 v[66:67], v[78:81], off
	global_store_dwordx4 v[66:67], v[70:73], off offset:16
; __device__ __forceinline__ u32x4 pack8(const f32x4 a, const f32x4 b) { u32x4 w; w.x = cvt_pk_bf16(a[0], a[1]); w.y = cvt_pk_bf16(a[2], a[3]); w.z = cvt_pk_bf16(b[0], b[1]); w.w = cvt_pk_bf16(b[2], b[3]); return w; }
;     __device__ __forceinline__ void operator()(const f32x4 (&acc)[2][2][4][2], const Unit& u, int wr, int wc, int fr, int fq) const {
;     ...
;         for (int ai = 0; ai < 2; ++ai) {
;             const int jb = u.pm * 4 + ai * 2 + wr;
;             f32x4 p1[2], p2[2];
; #pragma unroll
;             for (int n = 0; n < 2; ++n) { p1[n] = (f32x4){0.f, 0.f, 0.f, 0.f}; p2[n] = p1[n]; }
; #pragma unroll
;             for (int m = 0; m < 4; ++m) {
;                 f32x4 o[2];
; #pragma unroll
;                 for (int n = 0; n < 2; ++n) { f32x4 r1, r2;
; #pragma unroll
;                     for (int e = 0; e < 4; ++e) { const float a0 = acc[ai][0][m][n][e]; r1[e] = __shfl(a0, src1); r2[e] = __shfl(a0, src2); }
;                     f32x4 a1, a2;
; #pragma unroll
;                     for (int e = 0; e < 4; ++e) { a1[e] = fr >= 1 ? r1[e] : p1[n][e]; a2[e] = fr >= 2 ? r2[e] : p2[n][e]; }
;                     p1[n] = r1; p2[n] = r2;
;                     const f32x4 c = bb[n] + w0[n] * a2 + w1[n] * a1 + w2[n] * acc[ai][0][m][n];
; #pragma unroll
;                     for (int e = 0; e < 4; ++e) { const float x = c[e]; const float uu = 0.7978845608028654f * (x + 0.044715f * x * x * x);
;                         const float gl = x * __builtin_amdgcn_rcpf(1.f + __builtin_amdgcn_exp2f(-2.885390081777927f * uu)); o[n][e] = gl * acc[ai][1][m][n][e]; } }
;                 const int row = u.pm * BM + ai * HALF + wr * 64 + m * 16 + fr;
;                 if (!(m == 0 && fr < 2)) *(u32x4*)(G + (size_t)row * DFF + f0) = pack8(o[0], o[1]);
.LBB0_917:
	s_or_b64 exec, exec, s[70:71]
	s_nop 1
	v_mov_b32_dpp v76, v62 row_ror:1 row_mask:0xf bank_mask:0xf
	v_mov_b32_dpp v74, v62 row_ror:2 row_mask:0xf bank_mask:0xf
	v_mov_b32_dpp v77, v63 row_ror:1 row_mask:0xf bank_mask:0xf
	v_mov_b32_dpp v75, v63 row_ror:2 row_mask:0xf bank_mask:0xf
	v_mov_b32_dpp v72, v64 row_ror:1 row_mask:0xf bank_mask:0xf
	v_mov_b32_dpp v70, v64 row_ror:2 row_mask:0xf bank_mask:0xf
	v_mov_b32_dpp v73, v65 row_ror:1 row_mask:0xf bank_mask:0xf
	v_mov_b32_dpp v71, v65 row_ror:2 row_mask:0xf bank_mask:0xf
	v_mov_b32_dpp v68, v58 row_ror:1 row_mask:0xf bank_mask:0xf
	v_mov_b32_dpp v66, v58 row_ror:2 row_mask:0xf bank_mask:0xf
	v_mov_b32_dpp v69, v59 row_ror:1 row_mask:0xf bank_mask:0xf
	v_mov_b32_dpp v67, v59 row_ror:2 row_mask:0xf bank_mask:0xf
	v_mov_b32_dpp v80, v60 row_ror:1 row_mask:0xf bank_mask:0xf
	v_mov_b32_dpp v78, v60 row_ror:2 row_mask:0xf bank_mask:0xf
	v_mov_b32_dpp v81, v61 row_ror:1 row_mask:0xf bank_mask:0xf
	v_mov_b32_dpp v79, v61 row_ror:2 row_mask:0xf bank_mask:0xf
	s_and_saveexec_b64 s[68:69], s[8:9]
	s_xor_b64 s[68:69], exec, s[68:69]
	s_cbranch_execz .LBB0_919
	s_waitcnt lgkmcnt(0)
	v_pk_fma_f32 v[114:115], v[84:85], v[78:79], v[96:97]
	s_nop 0
	v_pk_fma_f32 v[114:115], v[88:89], v[80:81], v[114:115]
	s_nop 0
	v_pk_fma_f32 v[114:115], v[60:61], v[92:93], v[114:115]
	s_nop 0
	v_mul_f32_e32 v116, 0x3d372713, v115
	v_mul_f32_e32 v116, v115, v116
	v_mul_f32_e32 v117, 0x3d372713, v114
	v_fma_f32 v116, v115, v116, v115
	v_mul_f32_e32 v117, v114, v117
	v_mul_f32_e32 v116, 0x3f4c422a, v116
	v_fma_f32 v117, v114, v117, v114
	v_mul_f32_e32 v116, 0xc038aa3b, v116
	v_mul_f32_e32 v117, 0x3f4c422a, v117
	v_exp_f32_e32 v116, v116
	v_mul_f32_e32 v117, 0xc038aa3b, v117
	v_exp_f32_e32 v118, v117
	v_add_f32_e32 v116, 1.0, v116
	v_rcp_f32_e32 v117, v116
	v_add_f32_e32 v116, 1.0, v118
	v_rcp_f32_e32 v116, v116
	s_nop 0
	v_pk_mul_f32 v[114:115], v[114:115], v[116:117]
	v_pk_fma_f32 v[116:117], v[98:99], v[74:75], v[110:111]
	s_nop 0
	v_pk_fma_f32 v[116:117], v[102:103], v[76:77], v[116:117]
	s_nop 0
	v_pk_fma_f32 v[116:117], v[62:63], v[106:107], v[116:117]
	s_nop 0
	v_mul_f32_e32 v118, 0x3d372713, v116
	v_mul_f32_e32 v118, v116, v118
	v_fma_f32 v118, v116, v118, v116
	v_mul_f32_e32 v118, 0x3f4c422a, v118
	v_mul_f32_e32 v118, 0xc038aa3b, v118
	v_exp_f32_e32 v120, v118
	v_mul_f32_e32 v118, 0x3d372713, v117
	v_mul_f32_e32 v118, v117, v118
	v_fma_f32 v118, v117, v118, v117
	v_mul_f32_e32 v118, 0x3f4c422a, v118
	v_mul_f32_e32 v118, 0xc038aa3b, v118
	v_exp_f32_e32 v121, v118
	v_pk_mul_f32 v[118:119], v[52:53], v[114:115]
	v_add_f32_e32 v114, 1.0, v120
	v_rcp_f32_e32 v114, v114
	v_add_f32_e32 v115, 1.0, v121
	v_pk_fma_f32 v[120:121], v[100:101], v[70:71], v[112:113]
	v_rcp_f32_e32 v115, v115
	v_pk_fma_f32 v[120:121], v[104:105], v[72:73], v[120:121]
	v_pk_mul_f32 v[114:115], v[116:117], v[114:115]
	v_pk_fma_f32 v[120:121], v[64:65], v[108:109], v[120:121]
	v_pk_mul_f32 v[114:115], v[54:55], v[114:115]
	v_mul_f32_e32 v122, 0x3d372713, v120
	v_mul_f32_e32 v123, 0x3d372713, v121
	v_mul_f32_e32 v122, v120, v122
	v_mul_f32_e32 v123, v121, v123
	v_fma_f32 v122, v120, v122, v120
	v_fma_f32 v123, v121, v123, v121
	v_mul_f32_e32 v122, 0x3f4c422a, v122
	v_mul_f32_e32 v123, 0x3f4c422a, v123
	v_mul_f32_e32 v122, 0xc038aa3b, v122
	v_mul_f32_e32 v123, 0xc038aa3b, v123
	v_exp_f32_e32 v122, v122
	v_exp_f32_e32 v123, v123
	v_cvt_pk_bf16_f32 v114, v114, v115
	v_add_f32_e32 v116, 1.0, v122
	v_add_f32_e32 v117, 1.0, v123
	v_pk_fma_f32 v[122:123], v[82:83], v[66:67], v[94:95]
	v_rcp_f32_e32 v116, v116
	v_pk_fma_f32 v[122:123], v[86:87], v[68:69], v[122:123]
	v_rcp_f32_e32 v117, v117
	v_pk_fma_f32 v[122:123], v[58:59], v[90:91], v[122:123]
	v_pk_mul_f32 v[116:117], v[120:121], v[116:117]
	v_mul_f32_e32 v124, 0x3d372713, v123
	v_mul_f32_e32 v124, v123, v124
	v_mul_f32_e32 v125, 0x3d372713, v122
	v_fma_f32 v124, v123, v124, v123
	v_mul_f32_e32 v125, v122, v125
	v_mul_f32_e32 v124, 0x3f4c422a, v124
	v_fma_f32 v125, v122, v125, v122
	v_mul_f32_e32 v124, 0xc038aa3b, v124
	v_mul_f32_e32 v125, 0x3f4c422a, v125
	v_exp_f32_e32 v124, v124
	v_mul_f32_e32 v125, 0xc038aa3b, v125
	v_exp_f32_e32 v126, v125
	v_pk_mul_f32 v[116:117], v[56:57], v[116:117]
	v_add_f32_e32 v124, 1.0, v124
	v_rcp_f32_e32 v125, v124
	v_add_f32_e32 v124, 1.0, v126
	v_rcp_f32_e32 v124, v124
	v_cvt_pk_bf16_f32 v115, v116, v117
	v_cvt_pk_bf16_f32 v117, v118, v119
	v_mov_b64_e32 v[118:119], s[10:11]
	v_pk_mul_f32 v[120:121], v[122:123], v[124:125]
	v_add_u32_e32 v122, 0x80, v215
	v_pk_mul_f32 v[120:121], v[50:51], v[120:121]
	v_mad_i64_i32 v[118:119], s[70:71], v122, s79, v[118:119]
	v_cvt_pk_bf16_f32 v116, v120, v121
	v_lshl_add_u64 v[118:119], v[186:187], 1, v[118:119]
	global_store_dwordx4 v[118:119], v[114:117], off

; __device__ __forceinline__ u32x4 pack8(const f32x4 a, const f32x4 b) { u32x4 w; w.x = cvt_pk_bf16(a[0], a[1]); w.y = cvt_pk_bf16(a[2], a[3]); w.z = cvt_pk_bf16(b[0], b[1]); w.w = cvt_pk_bf16(b[2], b[3]); return w; }
;     __device__ __forceinline__ void operator()(const f32x4 (&acc)[2][2][4][2], const Unit& u, int wr, int wc, int fr, int fq) const {
;     ...
;             for (int m = 0; m < 4; ++m) {
;                 f32x4 o[2];
; #pragma unroll
;                 for (int n = 0; n < 2; ++n) { f32x4 r1, r2;
; #pragma unroll
;                     for (int e = 0; e < 4; ++e) { const float a0 = acc[ai][0][m][n][e]; r1[e] = __shfl(a0, src1); r2[e] = __shfl(a0, src2); }
;                     f32x4 a1, a2;
; #pragma unroll
;                     for (int e = 0; e < 4; ++e) { a1[e] = fr >= 1 ? r1[e] : p1[n][e]; a2[e] = fr >= 2 ? r2[e] : p2[n][e]; }
;                     p1[n] = r1; p2[n] = r2;
;                     const f32x4 c = bb[n] + w0[n] * a2 + w1[n] * a1 + w2[n] * acc[ai][0][m][n];
; #pragma unroll
;                     for (int e = 0; e < 4; ++e) { const float x = c[e]; const float uu = 0.7978845608028654f * (x + 0.044715f * x * x * x);
;                         const float gl = x * __builtin_amdgcn_rcpf(1.f + __builtin_amdgcn_exp2f(-2.885390081777927f * uu)); o[n][e] = gl * acc[ai][1][m][n][e]; } }
;                 const int row = u.pm * BM + ai * HALF + wr * 64 + m * 16 + fr;
;                 if (!(m == 0 && fr < 2)) *(u32x4*)(G + (size_t)row * DFF + f0) = pack8(o[0], o[1]);
.LBB0_921:
	s_or_b64 exec, exec, s[68:69]
	s_nop 1
	v_mov_b32_dpp v63, v45 row_ror:2 row_mask:0xf bank_mask:0xf
	v_mov_b32_dpp v64, v44 row_ror:2 row_mask:0xf bank_mask:0xf
	v_mov_b32_dpp v61, v45 row_ror:1 row_mask:0xf bank_mask:0xf
	v_mov_b32_dpp v62, v44 row_ror:1 row_mask:0xf bank_mask:0xf
	v_mov_b32_dpp v55, v46 row_ror:2 row_mask:0xf bank_mask:0xf
	s_waitcnt lgkmcnt(4)
	v_cndmask_b32_e64 v53, v79, v63, s[8:9]
	s_waitcnt lgkmcnt(3)
	v_cndmask_b32_e64 v52, v78, v64, s[8:9]
	s_waitcnt lgkmcnt(2)
	v_cndmask_b32_e64 v51, v61, v81, s[0:1]
	s_waitcnt lgkmcnt(1)
	v_cndmask_b32_e64 v50, v62, v80, s[0:1]
	v_pk_fma_f32 v[52:53], v[84:85], v[52:53], v[96:97]
	s_nop 1
	v_mov_b32_dpp v57, v47 row_ror:2 row_mask:0xf bank_mask:0xf
	v_pk_fma_f32 v[50:51], v[88:89], v[50:51], v[52:53]
	s_nop 1
	v_mov_b32_dpp v54, v46 row_ror:1 row_mask:0xf bank_mask:0xf
	v_pk_fma_f32 v[44:45], v[44:45], v[92:93], v[50:51]
	s_nop 1
	v_mov_b32_dpp v56, v47 row_ror:1 row_mask:0xf bank_mask:0xf
	v_mul_f32_e32 v50, 0x3d372713, v45
	v_mul_f32_e32 v50, v45, v50
	v_mul_f32_e32 v51, 0x3d372713, v44
	v_fma_f32 v50, v45, v50, v45
	v_mul_f32_e32 v51, v44, v51
	v_mul_f32_e32 v50, 0x3f4c422a, v50
	v_fma_f32 v51, v44, v51, v44
	v_mul_f32_e32 v50, 0xc038aa3b, v50
	v_mul_f32_e32 v51, 0x3f4c422a, v51
	v_exp_f32_e32 v50, v50
	v_mul_f32_e32 v51, 0xc038aa3b, v51
	v_exp_f32_e32 v52, v51
	s_waitcnt lgkmcnt(2)
	v_cndmask_b32_e64 v53, v75, v57, s[8:9]
	v_add_f32_e32 v50, 1.0, v50
	v_rcp_f32_e32 v51, v50
	v_add_f32_e32 v50, 1.0, v52
	v_rcp_f32_e32 v50, v50
	v_cndmask_b32_e64 v52, v74, v55, s[8:9]
	v_pk_fma_f32 v[52:53], v[98:99], v[52:53], v[110:111]
	s_nop 1
	v_mov_b32_dpp v59, v48 row_ror:2 row_mask:0xf bank_mask:0xf
	v_pk_mul_f32 v[44:45], v[44:45], v[50:51]
	s_waitcnt lgkmcnt(1)
	v_cndmask_b32_e64 v51, v56, v77, s[0:1]
	v_cndmask_b32_e64 v50, v54, v76, s[0:1]
	v_pk_fma_f32 v[50:51], v[102:103], v[50:51], v[52:53]
	s_nop 1
	v_mov_b32_dpp v65, v49 row_ror:2 row_mask:0xf bank_mask:0xf
	v_pk_fma_f32 v[46:47], v[46:47], v[106:107], v[50:51]
	s_nop 1
	v_mov_b32_dpp v58, v48 row_ror:1 row_mask:0xf bank_mask:0xf
	v_mul_f32_e32 v50, 0x3d372713, v46
	v_mul_f32_e32 v51, 0x3d372713, v47
	v_mul_f32_e32 v50, v46, v50
	v_mul_f32_e32 v51, v47, v51
	v_fma_f32 v50, v46, v50, v46
	v_fma_f32 v51, v47, v51, v47
	v_mul_f32_e32 v50, 0x3f4c422a, v50
	v_mul_f32_e32 v51, 0x3f4c422a, v51
	s_nop 1
	v_mov_b32_dpp v60, v49 row_ror:1 row_mask:0xf bank_mask:0xf
	v_mul_f32_e32 v50, 0xc038aa3b, v50
	v_mul_f32_e32 v51, 0xc038aa3b, v51
	v_exp_f32_e32 v50, v50
	v_exp_f32_e32 v51, v51
	s_waitcnt lgkmcnt(2)
	v_cndmask_b32_e64 v53, v71, v65, s[8:9]
	v_cndmask_b32_e64 v52, v70, v59, s[8:9]
	v_pk_mul_f32 v[44:45], v[36:37], v[44:45]
	v_add_f32_e32 v36, 1.0, v50
	v_add_f32_e32 v37, 1.0, v51
	s_waitcnt lgkmcnt(0)
	v_cndmask_b32_e64 v51, v60, v73, s[0:1]
	v_cndmask_b32_e64 v50, v58, v72, s[0:1]
	v_pk_fma_f32 v[52:53], v[100:101], v[52:53], v[112:113]
	s_nop 1
	v_mov_b32_dpp v79, v42 row_ror:2 row_mask:0xf bank_mask:0xf
	v_pk_fma_f32 v[50:51], v[104:105], v[50:51], v[52:53]
	s_nop 1
	v_mov_b32_dpp v81, v43 row_ror:2 row_mask:0xf bank_mask:0xf
	v_pk_fma_f32 v[48:49], v[48:49], v[108:109], v[50:51]
	s_nop 1
	v_mov_b32_dpp v78, v42 row_ror:1 row_mask:0xf bank_mask:0xf
	v_mul_f32_e32 v50, 0x3d372713, v48
	v_mul_f32_e32 v51, 0x3d372713, v49
	v_mul_f32_e32 v50, v48, v50
	v_mul_f32_e32 v51, v49, v51
	v_fma_f32 v50, v48, v50, v48
	v_fma_f32 v51, v49, v51, v49
	v_mul_f32_e32 v50, 0x3f4c422a, v50
	v_mul_f32_e32 v51, 0x3f4c422a, v51
	s_nop 1
	v_mov_b32_dpp v80, v43 row_ror:1 row_mask:0xf bank_mask:0xf
	v_mul_f32_e32 v50, 0xc038aa3b, v50
	v_mul_f32_e32 v51, 0xc038aa3b, v51
	v_rcp_f32_e32 v36, v36
	v_rcp_f32_e32 v37, v37
	v_exp_f32_e32 v50, v50
	v_exp_f32_e32 v51, v51
	s_waitcnt lgkmcnt(2)
	v_cndmask_b32_e64 v53, v67, v81, s[8:9]
	v_cndmask_b32_e64 v52, v66, v79, s[8:9]
	v_pk_mul_f32 v[36:37], v[46:47], v[36:37]
	v_add_f32_e32 v46, 1.0, v50
	v_add_f32_e32 v47, 1.0, v51
	s_waitcnt lgkmcnt(0)
	v_cndmask_b32_e64 v51, v80, v69, s[0:1]
	v_cndmask_b32_e64 v50, v78, v68, s[0:1]
	v_pk_fma_f32 v[52:53], v[82:83], v[52:53], v[94:95]
	v_rcp_f32_e32 v46, v46
	v_pk_fma_f32 v[50:51], v[86:87], v[50:51], v[52:53]
	v_rcp_f32_e32 v47, v47
	v_pk_fma_f32 v[42:43], v[42:43], v[90:91], v[50:51]
	v_pk_mul_f32 v[36:37], v[38:39], v[36:37]
	v_mul_f32_e32 v50, 0x3d372713, v43
	v_mul_f32_e32 v50, v43, v50
	v_mul_f32_e32 v51, 0x3d372713, v42
	v_fma_f32 v50, v43, v50, v43
	v_mul_f32_e32 v51, v42, v51
	v_mul_f32_e32 v50, 0x3f4c422a, v50
	v_fma_f32 v51, v42, v51, v42
	v_mul_f32_e32 v50, 0xc038aa3b, v50
	v_mul_f32_e32 v51, 0x3f4c422a, v51
	v_exp_f32_e32 v50, v50
	v_mul_f32_e32 v51, 0xc038aa3b, v51
	v_exp_f32_e32 v52, v51
	v_pk_mul_f32 v[38:39], v[48:49], v[46:47]
	v_add_f32_e32 v50, 1.0, v50
	v_rcp_f32_e32 v51, v50
	v_add_f32_e32 v50, 1.0, v52
	v_rcp_f32_e32 v50, v50
	v_pk_mul_f32 v[38:39], v[40:41], v[38:39]
	s_nop 1
	v_mov_b32_dpp v49, v29 row_ror:2 row_mask:0xf bank_mask:0xf
	v_mov_b32_dpp v47, v29 row_ror:1 row_mask:0xf bank_mask:0xf
	v_pk_mul_f32 v[40:41], v[42:43], v[50:51]
	s_nop 1
	v_mov_b32_dpp v50, v28 row_ror:2 row_mask:0xf bank_mask:0xf
	v_pk_mul_f32 v[34:35], v[34:35], v[40:41]
	s_nop 1
	v_mov_b32_dpp v48, v28 row_ror:1 row_mask:0xf bank_mask:0xf
	v_add_u32_e32 v40, 0x90, v215
	v_cvt_pk_bf16_f32 v36, v36, v37
	v_cvt_pk_bf16_f32 v37, v38, v39
	v_cvt_pk_bf16_f32 v38, v34, v35
	v_mov_b64_e32 v[34:35], s[10:11]
	v_mad_i64_i32 v[40:41], s[68:69], v40, s79, v[34:35]
	v_cvt_pk_bf16_f32 v39, v44, v45
	v_lshl_add_u64 v[40:41], v[40:41], 0, v[130:131]
	global_store_dwordx4 v[40:41], v[36:39], off
	s_nop 1
	v_mov_b32_dpp v41, v30 row_ror:2 row_mask:0xf bank_mask:0xf
	v_mov_b32_dpp v43, v31 row_ror:2 row_mask:0xf bank_mask:0xf
	s_waitcnt lgkmcnt(5)
; __device__ __forceinline__ u32x4 pack8(const f32x4 a, const f32x4 b) { u32x4 w; w.x = cvt_pk_bf16(a[0], a[1]); w.y = cvt_pk_bf16(a[2], a[3]); w.z = cvt_pk_bf16(b[0], b[1]); w.w = cvt_pk_bf16(b[2], b[3]); return w; }
;     __device__ __forceinline__ void operator()(const f32x4 (&acc)[2][2][4][2], const Unit& u, int wr, int wc, int fr, int fq) const {
;     ...
;             for (int m = 0; m < 4; ++m) {
;                 f32x4 o[2];
; #pragma unroll
;                 for (int n = 0; n < 2; ++n) { f32x4 r1, r2;
; #pragma unroll
;                     for (int e = 0; e < 4; ++e) { const float a0 = acc[ai][0][m][n][e]; r1[e] = __shfl(a0, src1); r2[e] = __shfl(a0, src2); }
;                     f32x4 a1, a2;
; #pragma unroll
;                     for (int e = 0; e < 4; ++e) { a1[e] = fr >= 1 ? r1[e] : p1[n][e]; a2[e] = fr >= 2 ? r2[e] : p2[n][e]; }
;                     p1[n] = r1; p2[n] = r2;
;                     const f32x4 c = bb[n] + w0[n] * a2 + w1[n] * a1 + w2[n] * acc[ai][0][m][n];
; #pragma unroll
;                     for (int e = 0; e < 4; ++e) { const float x = c[e]; const float uu = 0.7978845608028654f * (x + 0.044715f * x * x * x);
;                         const float gl = x * __builtin_amdgcn_rcpf(1.f + __builtin_amdgcn_exp2f(-2.885390081777927f * uu)); o[n][e] = gl * acc[ai][1][m][n][e]; } }
;                 const int row = u.pm * BM + ai * HALF + wr * 64 + m * 16 + fr;
;                 if (!(m == 0 && fr < 2)) *(u32x4*)(G + (size_t)row * DFF + f0) = pack8(o[0], o[1]);
	v_cndmask_b32_e64 v39, v63, v49, s[8:9]
	s_waitcnt lgkmcnt(3)
	v_cndmask_b32_e64 v38, v64, v50, s[8:9]
	v_cndmask_b32_e64 v37, v47, v61, s[0:1]
	s_waitcnt lgkmcnt(2)
	v_cndmask_b32_e64 v36, v48, v62, s[0:1]
	v_pk_fma_f32 v[38:39], v[84:85], v[38:39], v[96:97]
	s_nop 1
	v_mov_b32_dpp v40, v30 row_ror:1 row_mask:0xf bank_mask:0xf
	v_pk_fma_f32 v[36:37], v[88:89], v[36:37], v[38:39]
	s_nop 1
	v_mov_b32_dpp v42, v31 row_ror:1 row_mask:0xf bank_mask:0xf
	v_pk_fma_f32 v[28:29], v[28:29], v[92:93], v[36:37]
	s_waitcnt lgkmcnt(2)
	v_cndmask_b32_e64 v39, v57, v43, s[8:9]
	v_mul_f32_e32 v36, 0x3d372713, v29
	v_mul_f32_e32 v36, v29, v36
	v_mul_f32_e32 v37, 0x3d372713, v28
	v_fma_f32 v36, v29, v36, v29
	v_mul_f32_e32 v37, v28, v37
	v_mul_f32_e32 v36, 0x3f4c422a, v36
	v_fma_f32 v37, v28, v37, v28
	v_mul_f32_e32 v36, 0xc038aa3b, v36
	v_mul_f32_e32 v37, 0x3f4c422a, v37
	v_exp_f32_e32 v36, v36
	v_mul_f32_e32 v37, 0xc038aa3b, v37
	v_exp_f32_e32 v38, v37
	s_nop 1
	v_mov_b32_dpp v45, v32 row_ror:2 row_mask:0xf bank_mask:0xf
	v_add_f32_e32 v36, 1.0, v36
	v_rcp_f32_e32 v37, v36
	v_add_f32_e32 v36, 1.0, v38
	v_rcp_f32_e32 v36, v36
	v_cndmask_b32_e64 v38, v55, v41, s[8:9]
	v_pk_fma_f32 v[38:39], v[98:99], v[38:39], v[110:111]
	s_nop 1
	v_mov_b32_dpp v51, v33 row_ror:2 row_mask:0xf bank_mask:0xf
	v_pk_mul_f32 v[28:29], v[28:29], v[36:37]
	s_waitcnt lgkmcnt(2)
	v_cndmask_b32_e64 v37, v42, v56, s[0:1]
	v_cndmask_b32_e64 v36, v40, v54, s[0:1]
	v_pk_fma_f32 v[36:37], v[102:103], v[36:37], v[38:39]
	s_nop 1
	v_mov_b32_dpp v44, v32 row_ror:1 row_mask:0xf bank_mask:0xf
	v_pk_fma_f32 v[30:31], v[30:31], v[106:107], v[36:37]
	s_nop 1
	v_mov_b32_dpp v46, v33 row_ror:1 row_mask:0xf bank_mask:0xf
	v_mul_f32_e32 v36, 0x3d372713, v30
	v_mul_f32_e32 v37, 0x3d372713, v31
	v_mul_f32_e32 v36, v30, v36
	v_mul_f32_e32 v37, v31, v37
	v_fma_f32 v36, v30, v36, v30
	v_fma_f32 v37, v31, v37, v31
	v_mul_f32_e32 v36, 0x3f4c422a, v36
	v_mul_f32_e32 v37, 0x3f4c422a, v37
	v_mul_f32_e32 v36, 0xc038aa3b, v36
	v_mul_f32_e32 v37, 0xc038aa3b, v37
	v_exp_f32_e32 v36, v36
	v_exp_f32_e32 v37, v37
	s_waitcnt lgkmcnt(2)
	v_cndmask_b32_e64 v39, v65, v51, s[8:9]
	v_cndmask_b32_e64 v38, v59, v45, s[8:9]
	v_pk_mul_f32 v[28:29], v[20:21], v[28:29]
	v_add_f32_e32 v20, 1.0, v36
	v_add_f32_e32 v21, 1.0, v37
	s_waitcnt lgkmcnt(0)
	v_cndmask_b32_e64 v37, v46, v60, s[0:1]
	v_cndmask_b32_e64 v36, v44, v58, s[0:1]
	v_pk_fma_f32 v[38:39], v[100:101], v[38:39], v[112:113]
	s_nop 1
	v_mov_b32_dpp v53, v26 row_ror:2 row_mask:0xf bank_mask:0xf
	v_pk_fma_f32 v[36:37], v[104:105], v[36:37], v[38:39]
	s_nop 1
	v_mov_b32_dpp v62, v27 row_ror:2 row_mask:0xf bank_mask:0xf
	v_pk_fma_f32 v[32:33], v[32:33], v[108:109], v[36:37]
	s_nop 1
	v_mov_b32_dpp v52, v26 row_ror:1 row_mask:0xf bank_mask:0xf
	v_mul_f32_e32 v36, 0x3d372713, v32
	v_mul_f32_e32 v37, 0x3d372713, v33
	v_mul_f32_e32 v36, v32, v36
	v_mul_f32_e32 v37, v33, v37
	v_fma_f32 v36, v32, v36, v32
	v_fma_f32 v37, v33, v37, v33
	v_mul_f32_e32 v36, 0x3f4c422a, v36
	v_mul_f32_e32 v37, 0x3f4c422a, v37
	s_nop 1
	v_mov_b32_dpp v61, v27 row_ror:1 row_mask:0xf bank_mask:0xf
	v_mul_f32_e32 v36, 0xc038aa3b, v36
	v_mul_f32_e32 v37, 0xc038aa3b, v37
	v_rcp_f32_e32 v20, v20
	v_rcp_f32_e32 v21, v21
	v_exp_f32_e32 v36, v36
	v_exp_f32_e32 v37, v37
	s_waitcnt lgkmcnt(2)
	v_cndmask_b32_e64 v39, v81, v62, s[8:9]
	v_cndmask_b32_e64 v38, v79, v53, s[8:9]
	v_pk_mul_f32 v[20:21], v[30:31], v[20:21]
	v_add_f32_e32 v30, 1.0, v36
	v_add_f32_e32 v31, 1.0, v37
	s_waitcnt lgkmcnt(0)
	v_cndmask_b32_e64 v37, v61, v80, s[0:1]
	v_cndmask_b32_e64 v36, v52, v78, s[0:1]
	v_pk_fma_f32 v[38:39], v[82:83], v[38:39], v[94:95]
	v_rcp_f32_e32 v30, v30
	v_pk_fma_f32 v[36:37], v[86:87], v[36:37], v[38:39]
	v_rcp_f32_e32 v31, v31
	v_pk_fma_f32 v[26:27], v[26:27], v[90:91], v[36:37]
	v_pk_mul_f32 v[20:21], v[22:23], v[20:21]
	v_mul_f32_e32 v36, 0x3d372713, v27
	v_mul_f32_e32 v36, v27, v36
	v_mul_f32_e32 v37, 0x3d372713, v26
	v_fma_f32 v36, v27, v36, v27
	v_mul_f32_e32 v37, v26, v37
	v_mul_f32_e32 v36, 0x3f4c422a, v36
	v_fma_f32 v37, v26, v37, v26
	v_mul_f32_e32 v36, 0xc038aa3b, v36
	v_mul_f32_e32 v37, 0x3f4c422a, v37
	v_exp_f32_e32 v36, v36
	v_mul_f32_e32 v37, 0xc038aa3b, v37
	v_exp_f32_e32 v38, v37
	v_pk_mul_f32 v[22:23], v[32:33], v[30:31]
	v_add_f32_e32 v36, 1.0, v36
	v_rcp_f32_e32 v37, v36
	v_add_f32_e32 v36, 1.0, v38
	v_rcp_f32_e32 v36, v36
	v_pk_mul_f32 v[22:23], v[24:25], v[22:23]
	s_nop 1
	v_mov_b32_dpp v31, v8 row_ror:2 row_mask:0xf bank_mask:0xf
	v_mov_b32_dpp v33, v9 row_ror:2 row_mask:0xf bank_mask:0xf
	v_pk_mul_f32 v[24:25], v[26:27], v[36:37]
	v_add_u32_e32 v26, 0xa0, v215
	v_pk_mul_f32 v[24:25], v[18:19], v[24:25]
	v_cvt_pk_bf16_f32 v19, v22, v23
	v_mad_i64_i32 v[22:23], s[68:69], v26, s79, v[34:35]
	v_cvt_pk_bf16_f32 v18, v20, v21
	v_cvt_pk_bf16_f32 v20, v24, v25
	v_cvt_pk_bf16_f32 v21, v28, v29
	v_lshl_add_u64 v[22:23], v[22:23], 0, v[130:131]
	global_store_dwordx4 v[22:23], v[18:21], off
	s_nop 1
	v_mov_b32_dpp v20, v10 row_ror:2 row_mask:0xf bank_mask:0xf
	v_mov_b32_dpp v21, v11 row_ror:2 row_mask:0xf bank_mask:0xf
	v_mov_b32_dpp v18, v10 row_ror:1 row_mask:0xf bank_mask:0xf
	v_mov_b32_dpp v19, v11 row_ror:1 row_mask:0xf bank_mask:0xf
	v_mov_b32_dpp v22, v12 row_ror:1 row_mask:0xf bank_mask:0xf
	s_waitcnt lgkmcnt(4)
; __device__ __forceinline__ u32x4 pack8(const f32x4 a, const f32x4 b) { u32x4 w; w.x = cvt_pk_bf16(a[0], a[1]); w.y = cvt_pk_bf16(a[2], a[3]); w.z = cvt_pk_bf16(b[0], b[1]); w.w = cvt_pk_bf16(b[2], b[3]); return w; }
;     __device__ __forceinline__ void operator()(const f32x4 (&acc)[2][2][4][2], const Unit& u, int wr, int wc, int fr, int fq) const {
;     ...
;             for (int m = 0; m < 4; ++m) {
;                 f32x4 o[2];
; #pragma unroll
;                 for (int n = 0; n < 2; ++n) { f32x4 r1, r2;
; #pragma unroll
;                     for (int e = 0; e < 4; ++e) { const float a0 = acc[ai][0][m][n][e]; r1[e] = __shfl(a0, src1); r2[e] = __shfl(a0, src2); }
;                     f32x4 a1, a2;
; #pragma unroll
;                     for (int e = 0; e < 4; ++e) { a1[e] = fr >= 1 ? r1[e] : p1[n][e]; a2[e] = fr >= 2 ? r2[e] : p2[n][e]; }
;                     p1[n] = r1; p2[n] = r2;
;                     const f32x4 c = bb[n] + w0[n] * a2 + w1[n] * a1 + w2[n] * acc[ai][0][m][n];
; #pragma unroll
;                     for (int e = 0; e < 4; ++e) { const float x = c[e]; const float uu = 0.7978845608028654f * (x + 0.044715f * x * x * x);
;                         const float gl = x * __builtin_amdgcn_rcpf(1.f + __builtin_amdgcn_exp2f(-2.885390081777927f * uu)); o[n][e] = gl * acc[ai][1][m][n][e]; } }
;                 const int row = u.pm * BM + ai * HALF + wr * 64 + m * 16 + fr;
;                 if (!(m == 0 && fr < 2)) *(u32x4*)(G + (size_t)row * DFF + f0) = pack8(o[0], o[1]);
;                 if (m == 0 && fr < 2) { float* ah = AH + ((size_t)jb * 4 + 2 + fr) * DFF + f0; *(f32x4*)ah = acc[ai][0][0][0]; *(f32x4*)(ah + 4) = acc[ai][0][0][1];
;                     float* bh = BH + ((size_t)jb * 2 + fr) * DFF + f0; *(f32x4*)bh = acc[ai][1][0][0]; *(f32x4*)(bh + 4) = acc[ai][1][0][1]; }
;                 if (m == 3 && fr >= 14) { float* ah = AH + ((size_t)jb * 4 + (fr - 14)) * DFF + f0; *(f32x4*)ah = acc[ai][0][3][0]; *(f32x4*)(ah + 4) = acc[ai][0][3][1]; }
	v_cndmask_b32_e64 v20, v41, v20, s[8:9]
	s_waitcnt lgkmcnt(3)
	v_cndmask_b32_e64 v21, v43, v21, s[8:9]
	s_waitcnt lgkmcnt(2)
	v_cndmask_b32_e64 v18, v18, v40, s[0:1]
	s_waitcnt lgkmcnt(1)
	v_cndmask_b32_e64 v19, v19, v42, s[0:1]
	v_pk_fma_f32 v[20:21], v[98:99], v[20:21], v[110:111]
	s_nop 1
	v_mov_b32_dpp v24, v12 row_ror:2 row_mask:0xf bank_mask:0xf
	v_pk_fma_f32 v[18:19], v[102:103], v[18:19], v[20:21]
	s_nop 1
	v_mov_b32_dpp v23, v13 row_ror:1 row_mask:0xf bank_mask:0xf
	v_pk_fma_f32 v[18:19], v[10:11], v[106:107], v[18:19]
	s_nop 1
	v_mov_b32_dpp v25, v13 row_ror:2 row_mask:0xf bank_mask:0xf
	v_mul_f32_e32 v20, 0x3d372713, v18
	v_mul_f32_e32 v21, 0x3d372713, v19
	v_mul_f32_e32 v20, v18, v20
	v_mul_f32_e32 v21, v19, v21
	v_fma_f32 v20, v18, v20, v18
	v_fma_f32 v21, v19, v21, v19
	v_mul_f32_e32 v20, 0x3f4c422a, v20
	v_mul_f32_e32 v21, 0x3f4c422a, v21
	v_mul_f32_e32 v20, 0xc038aa3b, v20
	v_mul_f32_e32 v21, 0xc038aa3b, v21
	v_exp_f32_e32 v20, v20
	v_exp_f32_e32 v21, v21
	s_nop 1
	v_mov_b32_dpp v27, v6 row_ror:2 row_mask:0xf bank_mask:0xf
	v_mov_b32_dpp v29, v7 row_ror:2 row_mask:0xf bank_mask:0xf
	v_add_f32_e32 v20, 1.0, v20
	v_add_f32_e32 v21, 1.0, v21
	v_rcp_f32_e32 v20, v20
	v_rcp_f32_e32 v21, v21
	s_nop 1
	v_mov_b32_dpp v26, v6 row_ror:1 row_mask:0xf bank_mask:0xf
	v_mov_b32_dpp v28, v7 row_ror:1 row_mask:0xf bank_mask:0xf
	v_mov_b32_dpp v30, v8 row_ror:1 row_mask:0xf bank_mask:0xf
	v_pk_mul_f32 v[18:19], v[18:19], v[20:21]
	s_waitcnt lgkmcnt(6)
	v_cndmask_b32_e64 v21, v23, v46, s[0:1]
	v_cndmask_b32_e64 v20, v22, v44, s[0:1]
	s_waitcnt lgkmcnt(5)
	v_cndmask_b32_e64 v23, v51, v25, s[8:9]
	v_cndmask_b32_e64 v22, v45, v24, s[8:9]
	v_pk_fma_f32 v[22:23], v[100:101], v[22:23], v[112:113]
	s_waitcnt lgkmcnt(3)
	v_cndmask_b32_e64 v25, v62, v29, s[8:9]
	v_pk_fma_f32 v[20:21], v[104:105], v[20:21], v[22:23]
	v_cndmask_b32_e64 v24, v53, v27, s[8:9]
	v_pk_fma_f32 v[20:21], v[12:13], v[108:109], v[20:21]
	v_pk_mul_f32 v[14:15], v[14:15], v[18:19]
	v_mul_f32_e32 v22, 0x3d372713, v20
	v_mul_f32_e32 v23, 0x3d372713, v21
	v_mul_f32_e32 v22, v20, v22
	v_mul_f32_e32 v23, v21, v23
	v_fma_f32 v22, v20, v22, v20
	v_fma_f32 v23, v21, v23, v21
	v_mul_f32_e32 v22, 0x3f4c422a, v22
	v_mul_f32_e32 v23, 0x3f4c422a, v23
	v_mul_f32_e32 v22, 0xc038aa3b, v22
	v_mul_f32_e32 v23, 0xc038aa3b, v23
	v_exp_f32_e32 v22, v22
	v_exp_f32_e32 v23, v23
	v_pk_fma_f32 v[24:25], v[82:83], v[24:25], v[94:95]
	s_nop 1
	v_mov_b32_dpp v32, v9 row_ror:1 row_mask:0xf bank_mask:0xf
	v_add_f32_e32 v18, 1.0, v22
	v_add_f32_e32 v19, 1.0, v23
	s_waitcnt lgkmcnt(2)
	v_cndmask_b32_e64 v23, v28, v61, s[0:1]
	v_cndmask_b32_e64 v22, v26, v52, s[0:1]
	v_pk_fma_f32 v[22:23], v[86:87], v[22:23], v[24:25]
	v_rcp_f32_e32 v18, v18
	v_pk_fma_f32 v[22:23], v[6:7], v[90:91], v[22:23]
	v_rcp_f32_e32 v19, v19
	v_mul_f32_e32 v24, 0x3d372713, v22
	v_mul_f32_e32 v25, 0x3d372713, v23
	v_mul_f32_e32 v24, v22, v24
	v_mul_f32_e32 v25, v23, v25
	v_fma_f32 v24, v22, v24, v22
	v_fma_f32 v25, v23, v25, v23
	v_mul_f32_e32 v24, 0x3f4c422a, v24
	v_mul_f32_e32 v25, 0x3f4c422a, v25
	v_mul_f32_e32 v24, 0xc038aa3b, v24
	v_mul_f32_e32 v25, 0xc038aa3b, v25
	v_exp_f32_e32 v24, v24
	v_exp_f32_e32 v25, v25
	v_cndmask_b32_e64 v27, v49, v33, s[8:9]
	v_cndmask_b32_e64 v26, v50, v31, s[8:9]
	v_pk_mul_f32 v[18:19], v[20:21], v[18:19]
	v_add_f32_e32 v20, 1.0, v24
	v_add_f32_e32 v21, 1.0, v25
	s_waitcnt lgkmcnt(0)
	v_cndmask_b32_e64 v25, v32, v47, s[0:1]
	v_cndmask_b32_e64 v24, v30, v48, s[0:1]
	v_pk_fma_f32 v[26:27], v[84:85], v[26:27], v[96:97]
	v_rcp_f32_e32 v20, v20
	v_pk_fma_f32 v[24:25], v[88:89], v[24:25], v[26:27]
	v_rcp_f32_e32 v21, v21
	v_pk_fma_f32 v[24:25], v[8:9], v[92:93], v[24:25]
	v_pk_mul_f32 v[16:17], v[16:17], v[18:19]
	v_mul_f32_e32 v26, 0x3d372713, v25
	v_mul_f32_e32 v26, v25, v26
	v_mul_f32_e32 v27, 0x3d372713, v24
	v_fma_f32 v26, v25, v26, v25
	v_mul_f32_e32 v27, v24, v27
	v_mul_f32_e32 v26, 0x3f4c422a, v26
	v_fma_f32 v27, v24, v27, v24
	v_mul_f32_e32 v26, 0xc038aa3b, v26
	v_mul_f32_e32 v27, 0x3f4c422a, v27
	v_exp_f32_e32 v26, v26
	v_mul_f32_e32 v27, 0xc038aa3b, v27
	v_exp_f32_e32 v28, v27
	v_pk_mul_f32 v[18:19], v[22:23], v[20:21]
	v_add_f32_e32 v26, 1.0, v26
	v_rcp_f32_e32 v27, v26
	v_add_f32_e32 v26, 1.0, v28
	v_rcp_f32_e32 v26, v26
	v_pk_mul_f32 v[18:19], v[2:3], v[18:19]
	v_add_u32_e32 v22, 0xb0, v215
	v_pk_mul_f32 v[2:3], v[24:25], v[26:27]
	s_nop 0
	v_pk_mul_f32 v[20:21], v[4:5], v[2:3]
	v_cvt_pk_bf16_f32 v2, v14, v15
	v_mad_i64_i32 v[14:15], s[68:69], v22, s79, v[34:35]
	v_cvt_pk_bf16_f32 v3, v16, v17
	v_cvt_pk_bf16_f32 v4, v18, v19
	v_cvt_pk_bf16_f32 v5, v20, v21
	v_lshl_add_u64 v[14:15], v[14:15], 0, v[130:131]
	global_store_dwordx4 v[14:15], v[2:5], off
	s_and_saveexec_b64 s[68:69], s[4:5]
	s_cbranch_execz .LBB0_923
	v_lshl_add_u64 v[2:3], s[66:67], 0, v[176:177]
	v_mov_b64_e32 v[4:5], s[14:15]
	v_mad_u64_u32 v[4:5], s[66:67], v2, s80, v[4:5]
	v_mad_i32_i24 v5, v3, s80, v5
	v_lshl_add_u64 v[2:3], v[186:187], 2, v[4:5]
	global_store_dwordx4 v[2:3], v[10:13], off
	global_store_dwordx4 v[2:3], v[6:9], off offset:16
